# scan software-pipelined (31 loads in flight), in-proj rstd loads batched
# speedup vs baseline: 1.0006x; 1.0006x over previous
.LBB0_42:
	s_waitcnt lgkmcnt(0)
	s_add_u32 s22, s76, 0x2c180000
	s_addc_u32 s23, s77, 0
	v_lshrrev_b32_e32 v6, 12, v2
	v_lshlrev_b32_e32 v6, 2, v6
	v_lshl_add_u32 v6, v222, 7, v6
	v_add_u32_e32 v7, 0x2000, v6
	global_load_dword v8, v6, s[22:23]
	global_load_dword v9, v7, s[22:23]
	s_add_u32 s22, s76, 0x28180000
	s_addc_u32 s23, s77, 0
	s_mov_b32 s100, s22
	s_mov_b32 s101, s23
	v_mov_b32_e32 v10, 0
	v_mov_b32_e32 v11, 0
	global_load_dword v64, v4, s[22:23]
	s_add_u32 s22, s22, 0x80000
	s_addc_u32 s23, s23, 0
	global_load_dword v65, v4, s[22:23]
	s_add_u32 s22, s22, 0x80000
	s_addc_u32 s23, s23, 0
	global_load_dword v66, v4, s[22:23]
	s_add_u32 s22, s22, 0x80000
	s_addc_u32 s23, s23, 0
	global_load_dword v67, v4, s[22:23]
	s_add_u32 s22, s22, 0x80000
	s_addc_u32 s23, s23, 0
	global_load_dword v68, v4, s[22:23]
	s_add_u32 s22, s22, 0x80000
	s_addc_u32 s23, s23, 0
	global_load_dword v69, v4, s[22:23]
	s_add_u32 s22, s22, 0x80000
	s_addc_u32 s23, s23, 0
	global_load_dword v70, v4, s[22:23]
	s_add_u32 s22, s22, 0x80000
	s_addc_u32 s23, s23, 0
	global_load_dword v71, v4, s[22:23]
	s_add_u32 s22, s22, 0x80000
	s_addc_u32 s23, s23, 0
	global_load_dword v72, v4, s[22:23]
	s_add_u32 s22, s22, 0x80000
	s_addc_u32 s23, s23, 0
	global_load_dword v73, v4, s[22:23]
	s_add_u32 s22, s22, 0x80000
	s_addc_u32 s23, s23, 0
	global_load_dword v74, v4, s[22:23]
	s_add_u32 s22, s22, 0x80000
	s_addc_u32 s23, s23, 0
	global_load_dword v75, v4, s[22:23]
	s_add_u32 s22, s22, 0x80000
	s_addc_u32 s23, s23, 0
	global_load_dword v76, v4, s[22:23]
	s_add_u32 s22, s22, 0x80000
	s_addc_u32 s23, s23, 0
	global_load_dword v77, v4, s[22:23]
	s_add_u32 s22, s22, 0x80000
	s_addc_u32 s23, s23, 0
	global_load_dword v78, v4, s[22:23]
	s_add_u32 s22, s22, 0x80000
	s_addc_u32 s23, s23, 0
	global_load_dword v79, v4, s[22:23]
	s_add_u32 s22, s22, 0x80000
	s_addc_u32 s23, s23, 0
	global_load_dword v80, v4, s[22:23]
	s_add_u32 s22, s22, 0x80000
	s_addc_u32 s23, s23, 0
	global_load_dword v81, v4, s[22:23]
	s_add_u32 s22, s22, 0x80000
	s_addc_u32 s23, s23, 0
	global_load_dword v82, v4, s[22:23]
	s_add_u32 s22, s22, 0x80000
	s_addc_u32 s23, s23, 0
	global_load_dword v83, v4, s[22:23]
	s_add_u32 s22, s22, 0x80000
	s_addc_u32 s23, s23, 0
	global_load_dword v84, v4, s[22:23]
	s_add_u32 s22, s22, 0x80000
	s_addc_u32 s23, s23, 0
	global_load_dword v85, v4, s[22:23]
	s_add_u32 s22, s22, 0x80000
	s_addc_u32 s23, s23, 0
	global_load_dword v86, v4, s[22:23]
	s_add_u32 s22, s22, 0x80000
	s_addc_u32 s23, s23, 0
	global_load_dword v87, v4, s[22:23]
	s_add_u32 s22, s22, 0x80000
	s_addc_u32 s23, s23, 0
	global_load_dword v88, v4, s[22:23]
	s_add_u32 s22, s22, 0x80000
	s_addc_u32 s23, s23, 0
	global_load_dword v89, v4, s[22:23]
	s_add_u32 s22, s22, 0x80000
	s_addc_u32 s23, s23, 0
	global_load_dword v90, v4, s[22:23]
	s_add_u32 s22, s22, 0x80000
	s_addc_u32 s23, s23, 0
	global_load_dword v91, v4, s[22:23]
	s_add_u32 s22, s22, 0x80000
	s_addc_u32 s23, s23, 0
	global_load_dword v92, v4, s[22:23]
	s_add_u32 s22, s22, 0x80000
	s_addc_u32 s23, s23, 0
	global_load_dword v93, v4, s[22:23]
	s_add_u32 s22, s22, 0x80000
	s_addc_u32 s23, s23, 0
	global_load_dword v94, v4, s[22:23]
	s_add_u32 s22, s22, 0x80000
	s_addc_u32 s23, s23, 0
	s_waitcnt vmcnt(31)
	v_readlane_b32 s12, v8, 0
	s_waitcnt vmcnt(30)
	v_lshlrev_b32_e32 v12, 16, v64
	v_and_b32_e32 v13, 0xffff0000, v64
	v_cvt_pk_bf16_f32 v64, v10, v11
	v_fma_f32 v10, v10, s12, v12
	v_fma_f32 v11, v11, s12, v13
	v_readlane_b32 s13, v8, 1
	global_store_dword v4, v64, s[100:101]
	s_add_u32 s100, s100, 0x80000
	s_addc_u32 s101, s101, 0
	global_load_dword v95, v4, s[22:23]
	s_add_u32 s22, s22, 0x80000
	s_addc_u32 s23, s23, 0
	s_waitcnt vmcnt(31)
	v_lshlrev_b32_e32 v12, 16, v65
	v_and_b32_e32 v13, 0xffff0000, v65
	v_cvt_pk_bf16_f32 v65, v10, v11
	v_fma_f32 v10, v10, s13, v12
	v_fma_f32 v11, v11, s13, v13
	v_readlane_b32 s12, v8, 2
	global_store_dword v4, v65, s[100:101]
	s_add_u32 s100, s100, 0x80000
	s_addc_u32 s101, s101, 0
	global_load_dword v96, v4, s[22:23]
	s_add_u32 s22, s22, 0x80000
	s_addc_u32 s23, s23, 0
	s_waitcnt vmcnt(32)
	v_lshlrev_b32_e32 v12, 16, v66
	v_and_b32_e32 v13, 0xffff0000, v66
	v_cvt_pk_bf16_f32 v66, v10, v11
	v_fma_f32 v10, v10, s12, v12
	v_fma_f32 v11, v11, s12, v13
	v_readlane_b32 s13, v8, 3
	global_store_dword v4, v66, s[100:101]
	s_add_u32 s100, s100, 0x80000
	s_addc_u32 s101, s101, 0
	global_load_dword v97, v4, s[22:23]
	s_add_u32 s22, s22, 0x80000
	s_addc_u32 s23, s23, 0
	s_waitcnt vmcnt(33)
	v_lshlrev_b32_e32 v12, 16, v67
	v_and_b32_e32 v13, 0xffff0000, v67
	v_cvt_pk_bf16_f32 v67, v10, v11
	v_fma_f32 v10, v10, s13, v12
	v_fma_f32 v11, v11, s13, v13
	v_readlane_b32 s12, v8, 4
	global_store_dword v4, v67, s[100:101]
	s_add_u32 s100, s100, 0x80000
	s_addc_u32 s101, s101, 0
	global_load_dword v98, v4, s[22:23]
	s_add_u32 s22, s22, 0x80000
	s_addc_u32 s23, s23, 0
	s_waitcnt vmcnt(34)
	v_lshlrev_b32_e32 v12, 16, v68
	v_and_b32_e32 v13, 0xffff0000, v68
	v_cvt_pk_bf16_f32 v68, v10, v11
	v_fma_f32 v10, v10, s12, v12
	v_fma_f32 v11, v11, s12, v13
	v_readlane_b32 s13, v8, 5
	global_store_dword v4, v68, s[100:101]
	s_add_u32 s100, s100, 0x80000
	s_addc_u32 s101, s101, 0
	global_load_dword v99, v4, s[22:23]
	s_add_u32 s22, s22, 0x80000
	s_addc_u32 s23, s23, 0
	s_waitcnt vmcnt(35)
	v_lshlrev_b32_e32 v12, 16, v69
	v_and_b32_e32 v13, 0xffff0000, v69
	v_cvt_pk_bf16_f32 v69, v10, v11
	v_fma_f32 v10, v10, s13, v12
	v_fma_f32 v11, v11, s13, v13
	v_readlane_b32 s12, v8, 6
	global_store_dword v4, v69, s[100:101]
	s_add_u32 s100, s100, 0x80000
	s_addc_u32 s101, s101, 0
	global_load_dword v100, v4, s[22:23]
	s_add_u32 s22, s22, 0x80000
	s_addc_u32 s23, s23, 0
	s_waitcnt vmcnt(36)
	v_lshlrev_b32_e32 v12, 16, v70
	v_and_b32_e32 v13, 0xffff0000, v70
	v_cvt_pk_bf16_f32 v70, v10, v11
	v_fma_f32 v10, v10, s12, v12
	v_fma_f32 v11, v11, s12, v13
	v_readlane_b32 s13, v8, 7
	global_store_dword v4, v70, s[100:101]
	s_add_u32 s100, s100, 0x80000
	s_addc_u32 s101, s101, 0
	global_load_dword v101, v4, s[22:23]
	s_add_u32 s22, s22, 0x80000
	s_addc_u32 s23, s23, 0
	s_waitcnt vmcnt(37)
	v_lshlrev_b32_e32 v12, 16, v71
	v_and_b32_e32 v13, 0xffff0000, v71
	v_cvt_pk_bf16_f32 v71, v10, v11
	v_fma_f32 v10, v10, s13, v12
	v_fma_f32 v11, v11, s13, v13
	v_readlane_b32 s12, v8, 8
	global_store_dword v4, v71, s[100:101]
	s_add_u32 s100, s100, 0x80000
	s_addc_u32 s101, s101, 0
	global_load_dword v102, v4, s[22:23]
	s_add_u32 s22, s22, 0x80000
	s_addc_u32 s23, s23, 0
	s_waitcnt vmcnt(38)
	v_lshlrev_b32_e32 v12, 16, v72
	v_and_b32_e32 v13, 0xffff0000, v72
	v_cvt_pk_bf16_f32 v72, v10, v11
	v_fma_f32 v10, v10, s12, v12
	v_fma_f32 v11, v11, s12, v13
	v_readlane_b32 s13, v8, 9
	global_store_dword v4, v72, s[100:101]
	s_add_u32 s100, s100, 0x80000
	s_addc_u32 s101, s101, 0
	global_load_dword v103, v4, s[22:23]
	s_add_u32 s22, s22, 0x80000
	s_addc_u32 s23, s23, 0
	s_waitcnt vmcnt(39)
	v_lshlrev_b32_e32 v12, 16, v73
	v_and_b32_e32 v13, 0xffff0000, v73
	v_cvt_pk_bf16_f32 v73, v10, v11
	v_fma_f32 v10, v10, s13, v12
	v_fma_f32 v11, v11, s13, v13
	v_readlane_b32 s12, v8, 10
	global_store_dword v4, v73, s[100:101]
	s_add_u32 s100, s100, 0x80000
	s_addc_u32 s101, s101, 0
	global_load_dword v104, v4, s[22:23]
	s_add_u32 s22, s22, 0x80000
	s_addc_u32 s23, s23, 0
	s_waitcnt vmcnt(40)
	v_lshlrev_b32_e32 v12, 16, v74
	v_and_b32_e32 v13, 0xffff0000, v74
	v_cvt_pk_bf16_f32 v74, v10, v11
	v_fma_f32 v10, v10, s12, v12
	v_fma_f32 v11, v11, s12, v13
	v_readlane_b32 s13, v8, 11
	global_store_dword v4, v74, s[100:101]
	s_add_u32 s100, s100, 0x80000
	s_addc_u32 s101, s101, 0
	global_load_dword v105, v4, s[22:23]
	s_add_u32 s22, s22, 0x80000
	s_addc_u32 s23, s23, 0
	s_waitcnt vmcnt(41)
	v_lshlrev_b32_e32 v12, 16, v75
	v_and_b32_e32 v13, 0xffff0000, v75
	v_cvt_pk_bf16_f32 v75, v10, v11
	v_fma_f32 v10, v10, s13, v12
	v_fma_f32 v11, v11, s13, v13
	v_readlane_b32 s12, v8, 12
	global_store_dword v4, v75, s[100:101]
	s_add_u32 s100, s100, 0x80000
	s_addc_u32 s101, s101, 0
	global_load_dword v106, v4, s[22:23]
	s_add_u32 s22, s22, 0x80000
	s_addc_u32 s23, s23, 0
	s_waitcnt vmcnt(42)
	v_lshlrev_b32_e32 v12, 16, v76
	v_and_b32_e32 v13, 0xffff0000, v76
	v_cvt_pk_bf16_f32 v76, v10, v11
	v_fma_f32 v10, v10, s12, v12
	v_fma_f32 v11, v11, s12, v13
	v_readlane_b32 s13, v8, 13
	global_store_dword v4, v76, s[100:101]
	s_add_u32 s100, s100, 0x80000
	s_addc_u32 s101, s101, 0
	global_load_dword v107, v4, s[22:23]
	s_add_u32 s22, s22, 0x80000
	s_addc_u32 s23, s23, 0
	s_waitcnt vmcnt(43)
	v_lshlrev_b32_e32 v12, 16, v77
	v_and_b32_e32 v13, 0xffff0000, v77
	v_cvt_pk_bf16_f32 v77, v10, v11
	v_fma_f32 v10, v10, s13, v12
	v_fma_f32 v11, v11, s13, v13
	v_readlane_b32 s12, v8, 14
	global_store_dword v4, v77, s[100:101]
	s_add_u32 s100, s100, 0x80000
	s_addc_u32 s101, s101, 0
	global_load_dword v108, v4, s[22:23]
	s_add_u32 s22, s22, 0x80000
	s_addc_u32 s23, s23, 0
	s_waitcnt vmcnt(44)
	v_lshlrev_b32_e32 v12, 16, v78
	v_and_b32_e32 v13, 0xffff0000, v78
	v_cvt_pk_bf16_f32 v78, v10, v11
	v_fma_f32 v10, v10, s12, v12
	v_fma_f32 v11, v11, s12, v13
	v_readlane_b32 s13, v8, 15
	global_store_dword v4, v78, s[100:101]
	s_add_u32 s100, s100, 0x80000
	s_addc_u32 s101, s101, 0
	global_load_dword v109, v4, s[22:23]
	s_add_u32 s22, s22, 0x80000
	s_addc_u32 s23, s23, 0
	s_waitcnt vmcnt(45)
	v_lshlrev_b32_e32 v12, 16, v79
	v_and_b32_e32 v13, 0xffff0000, v79
	v_cvt_pk_bf16_f32 v79, v10, v11
	v_fma_f32 v10, v10, s13, v12
	v_fma_f32 v11, v11, s13, v13
	v_readlane_b32 s12, v8, 16
	global_store_dword v4, v79, s[100:101]
	s_add_u32 s100, s100, 0x80000
	s_addc_u32 s101, s101, 0
	global_load_dword v110, v4, s[22:23]
	s_add_u32 s22, s22, 0x80000
	s_addc_u32 s23, s23, 0
	s_waitcnt vmcnt(46)
	v_lshlrev_b32_e32 v12, 16, v80
	v_and_b32_e32 v13, 0xffff0000, v80
	v_cvt_pk_bf16_f32 v80, v10, v11
	v_fma_f32 v10, v10, s12, v12
	v_fma_f32 v11, v11, s12, v13
	v_readlane_b32 s13, v8, 17
	global_store_dword v4, v80, s[100:101]
	s_add_u32 s100, s100, 0x80000
	s_addc_u32 s101, s101, 0
	global_load_dword v111, v4, s[22:23]
	s_add_u32 s22, s22, 0x80000
	s_addc_u32 s23, s23, 0
	s_waitcnt vmcnt(47)
	v_lshlrev_b32_e32 v12, 16, v81
	v_and_b32_e32 v13, 0xffff0000, v81
	v_cvt_pk_bf16_f32 v81, v10, v11
	v_fma_f32 v10, v10, s13, v12
	v_fma_f32 v11, v11, s13, v13
	v_readlane_b32 s12, v8, 18
	global_store_dword v4, v81, s[100:101]
	s_add_u32 s100, s100, 0x80000
	s_addc_u32 s101, s101, 0
	global_load_dword v112, v4, s[22:23]
	s_add_u32 s22, s22, 0x80000
	s_addc_u32 s23, s23, 0
	s_waitcnt vmcnt(48)
	v_lshlrev_b32_e32 v12, 16, v82
	v_and_b32_e32 v13, 0xffff0000, v82
	v_cvt_pk_bf16_f32 v82, v10, v11
	v_fma_f32 v10, v10, s12, v12
	v_fma_f32 v11, v11, s12, v13
	v_readlane_b32 s13, v8, 19
	global_store_dword v4, v82, s[100:101]
	s_add_u32 s100, s100, 0x80000
	s_addc_u32 s101, s101, 0
	global_load_dword v113, v4, s[22:23]
	s_add_u32 s22, s22, 0x80000
	s_addc_u32 s23, s23, 0
	s_waitcnt vmcnt(49)
	v_lshlrev_b32_e32 v12, 16, v83
	v_and_b32_e32 v13, 0xffff0000, v83
	v_cvt_pk_bf16_f32 v83, v10, v11
	v_fma_f32 v10, v10, s13, v12
	v_fma_f32 v11, v11, s13, v13
	v_readlane_b32 s12, v8, 20
	global_store_dword v4, v83, s[100:101]
	s_add_u32 s100, s100, 0x80000
	s_addc_u32 s101, s101, 0
	global_load_dword v114, v4, s[22:23]
	s_add_u32 s22, s22, 0x80000
	s_addc_u32 s23, s23, 0
	s_waitcnt vmcnt(50)
	v_lshlrev_b32_e32 v12, 16, v84
	v_and_b32_e32 v13, 0xffff0000, v84
	v_cvt_pk_bf16_f32 v84, v10, v11
	v_fma_f32 v10, v10, s12, v12
	v_fma_f32 v11, v11, s12, v13
	v_readlane_b32 s13, v8, 21
	global_store_dword v4, v84, s[100:101]
	s_add_u32 s100, s100, 0x80000
	s_addc_u32 s101, s101, 0
	global_load_dword v115, v4, s[22:23]
	s_add_u32 s22, s22, 0x80000
	s_addc_u32 s23, s23, 0
	s_waitcnt vmcnt(51)
	v_lshlrev_b32_e32 v12, 16, v85
	v_and_b32_e32 v13, 0xffff0000, v85
	v_cvt_pk_bf16_f32 v85, v10, v11
	v_fma_f32 v10, v10, s13, v12
	v_fma_f32 v11, v11, s13, v13
	v_readlane_b32 s12, v8, 22
	global_store_dword v4, v85, s[100:101]
	s_add_u32 s100, s100, 0x80000
	s_addc_u32 s101, s101, 0
	global_load_dword v116, v4, s[22:23]
	s_add_u32 s22, s22, 0x80000
	s_addc_u32 s23, s23, 0
	s_waitcnt vmcnt(52)
	v_lshlrev_b32_e32 v12, 16, v86
	v_and_b32_e32 v13, 0xffff0000, v86
	v_cvt_pk_bf16_f32 v86, v10, v11
	v_fma_f32 v10, v10, s12, v12
	v_fma_f32 v11, v11, s12, v13
	v_readlane_b32 s13, v8, 23
	global_store_dword v4, v86, s[100:101]
	s_add_u32 s100, s100, 0x80000
	s_addc_u32 s101, s101, 0
	global_load_dword v117, v4, s[22:23]
	s_add_u32 s22, s22, 0x80000
	s_addc_u32 s23, s23, 0
	s_waitcnt vmcnt(53)
	v_lshlrev_b32_e32 v12, 16, v87
	v_and_b32_e32 v13, 0xffff0000, v87
	v_cvt_pk_bf16_f32 v87, v10, v11
	v_fma_f32 v10, v10, s13, v12
	v_fma_f32 v11, v11, s13, v13
	v_readlane_b32 s12, v8, 24
	global_store_dword v4, v87, s[100:101]
	s_add_u32 s100, s100, 0x80000
	s_addc_u32 s101, s101, 0
	global_load_dword v118, v4, s[22:23]
	s_add_u32 s22, s22, 0x80000
	s_addc_u32 s23, s23, 0
	s_waitcnt vmcnt(54)
	v_lshlrev_b32_e32 v12, 16, v88
	v_and_b32_e32 v13, 0xffff0000, v88
	v_cvt_pk_bf16_f32 v88, v10, v11
	v_fma_f32 v10, v10, s12, v12
	v_fma_f32 v11, v11, s12, v13
	v_readlane_b32 s13, v8, 25
	global_store_dword v4, v88, s[100:101]
	s_add_u32 s100, s100, 0x80000
	s_addc_u32 s101, s101, 0
	global_load_dword v119, v4, s[22:23]
	s_add_u32 s22, s22, 0x80000
	s_addc_u32 s23, s23, 0
	s_waitcnt vmcnt(55)
	v_lshlrev_b32_e32 v12, 16, v89
	v_and_b32_e32 v13, 0xffff0000, v89
	v_cvt_pk_bf16_f32 v89, v10, v11
	v_fma_f32 v10, v10, s13, v12
	v_fma_f32 v11, v11, s13, v13
	v_readlane_b32 s12, v8, 26
	global_store_dword v4, v89, s[100:101]
	s_add_u32 s100, s100, 0x80000
	s_addc_u32 s101, s101, 0
	global_load_dword v120, v4, s[22:23]
	s_add_u32 s22, s22, 0x80000
	s_addc_u32 s23, s23, 0
	s_waitcnt vmcnt(56)
	v_lshlrev_b32_e32 v12, 16, v90
	v_and_b32_e32 v13, 0xffff0000, v90
	v_cvt_pk_bf16_f32 v90, v10, v11
	v_fma_f32 v10, v10, s12, v12
	v_fma_f32 v11, v11, s12, v13
	v_readlane_b32 s13, v8, 27
	global_store_dword v4, v90, s[100:101]
	s_add_u32 s100, s100, 0x80000
	s_addc_u32 s101, s101, 0
	global_load_dword v121, v4, s[22:23]
	s_add_u32 s22, s22, 0x80000
	s_addc_u32 s23, s23, 0
	s_waitcnt vmcnt(57)
	v_lshlrev_b32_e32 v12, 16, v91
	v_and_b32_e32 v13, 0xffff0000, v91
	v_cvt_pk_bf16_f32 v91, v10, v11
	v_fma_f32 v10, v10, s13, v12
	v_fma_f32 v11, v11, s13, v13
	v_readlane_b32 s12, v8, 28
	global_store_dword v4, v91, s[100:101]
	s_add_u32 s100, s100, 0x80000
	s_addc_u32 s101, s101, 0
	global_load_dword v122, v4, s[22:23]
	s_add_u32 s22, s22, 0x80000
	s_addc_u32 s23, s23, 0
	s_waitcnt vmcnt(58)
	v_lshlrev_b32_e32 v12, 16, v92
	v_and_b32_e32 v13, 0xffff0000, v92
	v_cvt_pk_bf16_f32 v92, v10, v11
	v_fma_f32 v10, v10, s12, v12
	v_fma_f32 v11, v11, s12, v13
	v_readlane_b32 s13, v8, 29
	global_store_dword v4, v92, s[100:101]
	s_add_u32 s100, s100, 0x80000
	s_addc_u32 s101, s101, 0
	global_load_dword v123, v4, s[22:23]
	s_add_u32 s22, s22, 0x80000
	s_addc_u32 s23, s23, 0
	s_waitcnt vmcnt(59)
	v_lshlrev_b32_e32 v12, 16, v93
	v_and_b32_e32 v13, 0xffff0000, v93
	v_cvt_pk_bf16_f32 v93, v10, v11
	v_fma_f32 v10, v10, s13, v12
	v_fma_f32 v11, v11, s13, v13
	v_readlane_b32 s12, v8, 30
	global_store_dword v4, v93, s[100:101]
	s_add_u32 s100, s100, 0x80000
	s_addc_u32 s101, s101, 0
	global_load_dword v124, v4, s[22:23]
	s_add_u32 s22, s22, 0x80000
	s_addc_u32 s23, s23, 0
	s_waitcnt vmcnt(60)
	v_lshlrev_b32_e32 v12, 16, v94
	v_and_b32_e32 v13, 0xffff0000, v94
	v_cvt_pk_bf16_f32 v94, v10, v11
	v_fma_f32 v10, v10, s12, v12
	v_fma_f32 v11, v11, s12, v13
	v_readlane_b32 s13, v8, 31
	global_store_dword v4, v94, s[100:101]
	s_add_u32 s100, s100, 0x80000
	s_addc_u32 s101, s101, 0
	global_load_dword v125, v4, s[22:23]
	s_add_u32 s22, s22, 0x80000
	s_addc_u32 s23, s23, 0
	s_waitcnt vmcnt(60)
	v_lshlrev_b32_e32 v12, 16, v95
	v_and_b32_e32 v13, 0xffff0000, v95
	v_cvt_pk_bf16_f32 v95, v10, v11
	v_fma_f32 v10, v10, s13, v12
	v_fma_f32 v11, v11, s13, v13
	v_readlane_b32 s12, v8, 32
	global_store_dword v4, v95, s[100:101]
	s_add_u32 s100, s100, 0x80000
	s_addc_u32 s101, s101, 0
	global_load_dword v126, v4, s[22:23]
	s_add_u32 s22, s22, 0x80000
	s_addc_u32 s23, s23, 0
	s_waitcnt vmcnt(60)
	v_lshlrev_b32_e32 v12, 16, v96
	v_and_b32_e32 v13, 0xffff0000, v96
	v_cvt_pk_bf16_f32 v96, v10, v11
	v_fma_f32 v10, v10, s12, v12
	v_fma_f32 v11, v11, s12, v13
	v_readlane_b32 s13, v8, 33
	global_store_dword v4, v96, s[100:101]
	s_add_u32 s100, s100, 0x80000
	s_addc_u32 s101, s101, 0
	global_load_dword v127, v4, s[22:23]
	s_add_u32 s22, s22, 0x80000
	s_addc_u32 s23, s23, 0
	s_waitcnt vmcnt(60)
	v_lshlrev_b32_e32 v12, 16, v97
	v_and_b32_e32 v13, 0xffff0000, v97
	v_cvt_pk_bf16_f32 v97, v10, v11
	v_fma_f32 v10, v10, s13, v12
	v_fma_f32 v11, v11, s13, v13
	v_readlane_b32 s12, v8, 34
	global_store_dword v4, v97, s[100:101]
	s_add_u32 s100, s100, 0x80000
	s_addc_u32 s101, s101, 0
	global_load_dword v128, v4, s[22:23]
	s_add_u32 s22, s22, 0x80000
	s_addc_u32 s23, s23, 0
	s_waitcnt vmcnt(60)
	v_lshlrev_b32_e32 v12, 16, v98
	v_and_b32_e32 v13, 0xffff0000, v98
	v_cvt_pk_bf16_f32 v98, v10, v11
	v_fma_f32 v10, v10, s12, v12
	v_fma_f32 v11, v11, s12, v13
	v_readlane_b32 s13, v8, 35
	global_store_dword v4, v98, s[100:101]
	s_add_u32 s100, s100, 0x80000
	s_addc_u32 s101, s101, 0
	global_load_dword v129, v4, s[22:23]
	s_add_u32 s22, s22, 0x80000
	s_addc_u32 s23, s23, 0
	s_waitcnt vmcnt(60)
	v_lshlrev_b32_e32 v12, 16, v99
	v_and_b32_e32 v13, 0xffff0000, v99
	v_cvt_pk_bf16_f32 v99, v10, v11
	v_fma_f32 v10, v10, s13, v12
	v_fma_f32 v11, v11, s13, v13
	v_readlane_b32 s12, v8, 36
	global_store_dword v4, v99, s[100:101]
	s_add_u32 s100, s100, 0x80000
	s_addc_u32 s101, s101, 0
	global_load_dword v130, v4, s[22:23]
	s_add_u32 s22, s22, 0x80000
	s_addc_u32 s23, s23, 0
	s_waitcnt vmcnt(60)
	v_lshlrev_b32_e32 v12, 16, v100
	v_and_b32_e32 v13, 0xffff0000, v100
	v_cvt_pk_bf16_f32 v100, v10, v11
	v_fma_f32 v10, v10, s12, v12
	v_fma_f32 v11, v11, s12, v13
	v_readlane_b32 s13, v8, 37
	global_store_dword v4, v100, s[100:101]
	s_add_u32 s100, s100, 0x80000
	s_addc_u32 s101, s101, 0
	global_load_dword v131, v4, s[22:23]
	s_add_u32 s22, s22, 0x80000
	s_addc_u32 s23, s23, 0
	s_waitcnt vmcnt(60)
	v_lshlrev_b32_e32 v12, 16, v101
	v_and_b32_e32 v13, 0xffff0000, v101
	v_cvt_pk_bf16_f32 v101, v10, v11
	v_fma_f32 v10, v10, s13, v12
	v_fma_f32 v11, v11, s13, v13
	v_readlane_b32 s12, v8, 38
	global_store_dword v4, v101, s[100:101]
	s_add_u32 s100, s100, 0x80000
	s_addc_u32 s101, s101, 0
	global_load_dword v132, v4, s[22:23]
	s_add_u32 s22, s22, 0x80000
	s_addc_u32 s23, s23, 0
	s_waitcnt vmcnt(60)
	v_lshlrev_b32_e32 v12, 16, v102
	v_and_b32_e32 v13, 0xffff0000, v102
	v_cvt_pk_bf16_f32 v102, v10, v11
	v_fma_f32 v10, v10, s12, v12
	v_fma_f32 v11, v11, s12, v13
	v_readlane_b32 s13, v8, 39
	global_store_dword v4, v102, s[100:101]
	s_add_u32 s100, s100, 0x80000
	s_addc_u32 s101, s101, 0
	global_load_dword v133, v4, s[22:23]
	s_add_u32 s22, s22, 0x80000
	s_addc_u32 s23, s23, 0
	s_waitcnt vmcnt(60)
	v_lshlrev_b32_e32 v12, 16, v103
	v_and_b32_e32 v13, 0xffff0000, v103
	v_cvt_pk_bf16_f32 v103, v10, v11
	v_fma_f32 v10, v10, s13, v12
	v_fma_f32 v11, v11, s13, v13
	v_readlane_b32 s12, v8, 40
	global_store_dword v4, v103, s[100:101]
	s_add_u32 s100, s100, 0x80000
	s_addc_u32 s101, s101, 0
	global_load_dword v134, v4, s[22:23]
	s_add_u32 s22, s22, 0x80000
	s_addc_u32 s23, s23, 0
	s_waitcnt vmcnt(60)
	v_lshlrev_b32_e32 v12, 16, v104
	v_and_b32_e32 v13, 0xffff0000, v104
	v_cvt_pk_bf16_f32 v104, v10, v11
	v_fma_f32 v10, v10, s12, v12
	v_fma_f32 v11, v11, s12, v13
	v_readlane_b32 s13, v8, 41
	global_store_dword v4, v104, s[100:101]
	s_add_u32 s100, s100, 0x80000
	s_addc_u32 s101, s101, 0
	global_load_dword v135, v4, s[22:23]
	s_add_u32 s22, s22, 0x80000
	s_addc_u32 s23, s23, 0
	s_waitcnt vmcnt(60)
	v_lshlrev_b32_e32 v12, 16, v105
	v_and_b32_e32 v13, 0xffff0000, v105
	v_cvt_pk_bf16_f32 v105, v10, v11
	v_fma_f32 v10, v10, s13, v12
	v_fma_f32 v11, v11, s13, v13
	v_readlane_b32 s12, v8, 42
	global_store_dword v4, v105, s[100:101]
	s_add_u32 s100, s100, 0x80000
	s_addc_u32 s101, s101, 0
	global_load_dword v136, v4, s[22:23]
	s_add_u32 s22, s22, 0x80000
	s_addc_u32 s23, s23, 0
	s_waitcnt vmcnt(60)
	v_lshlrev_b32_e32 v12, 16, v106
	v_and_b32_e32 v13, 0xffff0000, v106
	v_cvt_pk_bf16_f32 v106, v10, v11
	v_fma_f32 v10, v10, s12, v12
	v_fma_f32 v11, v11, s12, v13
	v_readlane_b32 s13, v8, 43
	global_store_dword v4, v106, s[100:101]
	s_add_u32 s100, s100, 0x80000
	s_addc_u32 s101, s101, 0
	global_load_dword v137, v4, s[22:23]
	s_add_u32 s22, s22, 0x80000
	s_addc_u32 s23, s23, 0
	s_waitcnt vmcnt(60)
	v_lshlrev_b32_e32 v12, 16, v107
	v_and_b32_e32 v13, 0xffff0000, v107
	v_cvt_pk_bf16_f32 v107, v10, v11
	v_fma_f32 v10, v10, s13, v12
	v_fma_f32 v11, v11, s13, v13
	v_readlane_b32 s12, v8, 44
	global_store_dword v4, v107, s[100:101]
	s_add_u32 s100, s100, 0x80000
	s_addc_u32 s101, s101, 0
	global_load_dword v138, v4, s[22:23]
	s_add_u32 s22, s22, 0x80000
	s_addc_u32 s23, s23, 0
	s_waitcnt vmcnt(60)
	v_lshlrev_b32_e32 v12, 16, v108
	v_and_b32_e32 v13, 0xffff0000, v108
	v_cvt_pk_bf16_f32 v108, v10, v11
	v_fma_f32 v10, v10, s12, v12
	v_fma_f32 v11, v11, s12, v13
	v_readlane_b32 s13, v8, 45
	global_store_dword v4, v108, s[100:101]
	s_add_u32 s100, s100, 0x80000
	s_addc_u32 s101, s101, 0
	global_load_dword v139, v4, s[22:23]
	s_add_u32 s22, s22, 0x80000
	s_addc_u32 s23, s23, 0
	s_waitcnt vmcnt(60)
	v_lshlrev_b32_e32 v12, 16, v109
	v_and_b32_e32 v13, 0xffff0000, v109
	v_cvt_pk_bf16_f32 v109, v10, v11
	v_fma_f32 v10, v10, s13, v12
	v_fma_f32 v11, v11, s13, v13
	v_readlane_b32 s12, v8, 46
	global_store_dword v4, v109, s[100:101]
	s_add_u32 s100, s100, 0x80000
	s_addc_u32 s101, s101, 0
	global_load_dword v140, v4, s[22:23]
	s_add_u32 s22, s22, 0x80000
	s_addc_u32 s23, s23, 0
	s_waitcnt vmcnt(60)
	v_lshlrev_b32_e32 v12, 16, v110
	v_and_b32_e32 v13, 0xffff0000, v110
	v_cvt_pk_bf16_f32 v110, v10, v11
	v_fma_f32 v10, v10, s12, v12
	v_fma_f32 v11, v11, s12, v13
	v_readlane_b32 s13, v8, 47
	global_store_dword v4, v110, s[100:101]
	s_add_u32 s100, s100, 0x80000
	s_addc_u32 s101, s101, 0
	global_load_dword v141, v4, s[22:23]
	s_add_u32 s22, s22, 0x80000
	s_addc_u32 s23, s23, 0
	s_waitcnt vmcnt(60)
	v_lshlrev_b32_e32 v12, 16, v111
	v_and_b32_e32 v13, 0xffff0000, v111
	v_cvt_pk_bf16_f32 v111, v10, v11
	v_fma_f32 v10, v10, s13, v12
	v_fma_f32 v11, v11, s13, v13
	v_readlane_b32 s12, v8, 48
	global_store_dword v4, v111, s[100:101]
	s_add_u32 s100, s100, 0x80000
	s_addc_u32 s101, s101, 0
	global_load_dword v142, v4, s[22:23]
	s_add_u32 s22, s22, 0x80000
	s_addc_u32 s23, s23, 0
	s_waitcnt vmcnt(60)
	v_lshlrev_b32_e32 v12, 16, v112
	v_and_b32_e32 v13, 0xffff0000, v112
	v_cvt_pk_bf16_f32 v112, v10, v11
	v_fma_f32 v10, v10, s12, v12
	v_fma_f32 v11, v11, s12, v13
	v_readlane_b32 s13, v8, 49
	global_store_dword v4, v112, s[100:101]
	s_add_u32 s100, s100, 0x80000
	s_addc_u32 s101, s101, 0
	global_load_dword v143, v4, s[22:23]
	s_add_u32 s22, s22, 0x80000
	s_addc_u32 s23, s23, 0
	s_waitcnt vmcnt(60)
	v_lshlrev_b32_e32 v12, 16, v113
	v_and_b32_e32 v13, 0xffff0000, v113
	v_cvt_pk_bf16_f32 v113, v10, v11
	v_fma_f32 v10, v10, s13, v12
	v_fma_f32 v11, v11, s13, v13
	v_readlane_b32 s12, v8, 50
	global_store_dword v4, v113, s[100:101]
	s_add_u32 s100, s100, 0x80000
	s_addc_u32 s101, s101, 0
	global_load_dword v144, v4, s[22:23]
	s_add_u32 s22, s22, 0x80000
	s_addc_u32 s23, s23, 0
	s_waitcnt vmcnt(60)
	v_lshlrev_b32_e32 v12, 16, v114
	v_and_b32_e32 v13, 0xffff0000, v114
	v_cvt_pk_bf16_f32 v114, v10, v11
	v_fma_f32 v10, v10, s12, v12
	v_fma_f32 v11, v11, s12, v13
	v_readlane_b32 s13, v8, 51
	global_store_dword v4, v114, s[100:101]
	s_add_u32 s100, s100, 0x80000
	s_addc_u32 s101, s101, 0
	global_load_dword v145, v4, s[22:23]
	s_add_u32 s22, s22, 0x80000
	s_addc_u32 s23, s23, 0
	s_waitcnt vmcnt(60)
	v_lshlrev_b32_e32 v12, 16, v115
	v_and_b32_e32 v13, 0xffff0000, v115
	v_cvt_pk_bf16_f32 v115, v10, v11
	v_fma_f32 v10, v10, s13, v12
	v_fma_f32 v11, v11, s13, v13
	v_readlane_b32 s12, v8, 52
	global_store_dword v4, v115, s[100:101]
	s_add_u32 s100, s100, 0x80000
	s_addc_u32 s101, s101, 0
	global_load_dword v146, v4, s[22:23]
	s_add_u32 s22, s22, 0x80000
	s_addc_u32 s23, s23, 0
	s_waitcnt vmcnt(60)
	v_lshlrev_b32_e32 v12, 16, v116
	v_and_b32_e32 v13, 0xffff0000, v116
	v_cvt_pk_bf16_f32 v116, v10, v11
	v_fma_f32 v10, v10, s12, v12
	v_fma_f32 v11, v11, s12, v13
	v_readlane_b32 s13, v8, 53
	global_store_dword v4, v116, s[100:101]
	s_add_u32 s100, s100, 0x80000
	s_addc_u32 s101, s101, 0
	global_load_dword v147, v4, s[22:23]
	s_add_u32 s22, s22, 0x80000
	s_addc_u32 s23, s23, 0
	s_waitcnt vmcnt(60)
	v_lshlrev_b32_e32 v12, 16, v117
	v_and_b32_e32 v13, 0xffff0000, v117
	v_cvt_pk_bf16_f32 v117, v10, v11
	v_fma_f32 v10, v10, s13, v12
	v_fma_f32 v11, v11, s13, v13
	v_readlane_b32 s12, v8, 54
	global_store_dword v4, v117, s[100:101]
	s_add_u32 s100, s100, 0x80000
	s_addc_u32 s101, s101, 0
	global_load_dword v148, v4, s[22:23]
	s_add_u32 s22, s22, 0x80000
	s_addc_u32 s23, s23, 0
	s_waitcnt vmcnt(60)
	v_lshlrev_b32_e32 v12, 16, v118
	v_and_b32_e32 v13, 0xffff0000, v118
	v_cvt_pk_bf16_f32 v118, v10, v11
	v_fma_f32 v10, v10, s12, v12
	v_fma_f32 v11, v11, s12, v13
	v_readlane_b32 s13, v8, 55
	global_store_dword v4, v118, s[100:101]
	s_add_u32 s100, s100, 0x80000
	s_addc_u32 s101, s101, 0
	global_load_dword v149, v4, s[22:23]
	s_add_u32 s22, s22, 0x80000
	s_addc_u32 s23, s23, 0
	s_waitcnt vmcnt(60)
	v_lshlrev_b32_e32 v12, 16, v119
	v_and_b32_e32 v13, 0xffff0000, v119
	v_cvt_pk_bf16_f32 v119, v10, v11
	v_fma_f32 v10, v10, s13, v12
	v_fma_f32 v11, v11, s13, v13
	v_readlane_b32 s12, v8, 56
	global_store_dword v4, v119, s[100:101]
	s_add_u32 s100, s100, 0x80000
	s_addc_u32 s101, s101, 0
	global_load_dword v150, v4, s[22:23]
	s_add_u32 s22, s22, 0x80000
	s_addc_u32 s23, s23, 0
	s_waitcnt vmcnt(60)
	v_lshlrev_b32_e32 v12, 16, v120
	v_and_b32_e32 v13, 0xffff0000, v120
	v_cvt_pk_bf16_f32 v120, v10, v11
	v_fma_f32 v10, v10, s12, v12
	v_fma_f32 v11, v11, s12, v13
	v_readlane_b32 s13, v8, 57
	global_store_dword v4, v120, s[100:101]
	s_add_u32 s100, s100, 0x80000
	s_addc_u32 s101, s101, 0
	global_load_dword v151, v4, s[22:23]
	s_add_u32 s22, s22, 0x80000
	s_addc_u32 s23, s23, 0
	s_waitcnt vmcnt(60)
	v_lshlrev_b32_e32 v12, 16, v121
	v_and_b32_e32 v13, 0xffff0000, v121
	v_cvt_pk_bf16_f32 v121, v10, v11
	v_fma_f32 v10, v10, s13, v12
	v_fma_f32 v11, v11, s13, v13
	v_readlane_b32 s12, v8, 58
	global_store_dword v4, v121, s[100:101]
	s_add_u32 s100, s100, 0x80000
	s_addc_u32 s101, s101, 0
	global_load_dword v152, v4, s[22:23]
	s_add_u32 s22, s22, 0x80000
	s_addc_u32 s23, s23, 0
	s_waitcnt vmcnt(60)
	v_lshlrev_b32_e32 v12, 16, v122
	v_and_b32_e32 v13, 0xffff0000, v122
	v_cvt_pk_bf16_f32 v122, v10, v11
	v_fma_f32 v10, v10, s12, v12
	v_fma_f32 v11, v11, s12, v13
	v_readlane_b32 s13, v8, 59
	global_store_dword v4, v122, s[100:101]
	s_add_u32 s100, s100, 0x80000
	s_addc_u32 s101, s101, 0
	global_load_dword v153, v4, s[22:23]
	s_add_u32 s22, s22, 0x80000
	s_addc_u32 s23, s23, 0
	s_waitcnt vmcnt(60)
	v_lshlrev_b32_e32 v12, 16, v123
	v_and_b32_e32 v13, 0xffff0000, v123
	v_cvt_pk_bf16_f32 v123, v10, v11
	v_fma_f32 v10, v10, s13, v12
	v_fma_f32 v11, v11, s13, v13
	v_readlane_b32 s12, v8, 60
	global_store_dword v4, v123, s[100:101]
	s_add_u32 s100, s100, 0x80000
	s_addc_u32 s101, s101, 0
	global_load_dword v154, v4, s[22:23]
	s_add_u32 s22, s22, 0x80000
	s_addc_u32 s23, s23, 0
	s_waitcnt vmcnt(60)
	v_lshlrev_b32_e32 v12, 16, v124
	v_and_b32_e32 v13, 0xffff0000, v124
	v_cvt_pk_bf16_f32 v124, v10, v11
	v_fma_f32 v10, v10, s12, v12
	v_fma_f32 v11, v11, s12, v13
	v_readlane_b32 s13, v8, 61
	global_store_dword v4, v124, s[100:101]
	s_add_u32 s100, s100, 0x80000
	s_addc_u32 s101, s101, 0
	global_load_dword v155, v4, s[22:23]
	s_add_u32 s22, s22, 0x80000
	s_addc_u32 s23, s23, 0
	s_waitcnt vmcnt(60)
	v_lshlrev_b32_e32 v12, 16, v125
	v_and_b32_e32 v13, 0xffff0000, v125
	v_cvt_pk_bf16_f32 v125, v10, v11
	v_fma_f32 v10, v10, s13, v12
	v_fma_f32 v11, v11, s13, v13
	v_readlane_b32 s12, v8, 62
	global_store_dword v4, v125, s[100:101]
	s_add_u32 s100, s100, 0x80000
	s_addc_u32 s101, s101, 0
	global_load_dword v156, v4, s[22:23]
	s_add_u32 s22, s22, 0x80000
	s_addc_u32 s23, s23, 0
	s_waitcnt vmcnt(60)
	v_lshlrev_b32_e32 v12, 16, v126
	v_and_b32_e32 v13, 0xffff0000, v126
	v_cvt_pk_bf16_f32 v126, v10, v11
	v_fma_f32 v10, v10, s12, v12
	v_fma_f32 v11, v11, s12, v13
	v_readlane_b32 s13, v8, 63
	global_store_dword v4, v126, s[100:101]
	s_add_u32 s100, s100, 0x80000
	s_addc_u32 s101, s101, 0
	global_load_dword v157, v4, s[22:23]
	s_add_u32 s22, s22, 0x80000
	s_addc_u32 s23, s23, 0
	s_waitcnt vmcnt(60)
	v_lshlrev_b32_e32 v12, 16, v127
	v_and_b32_e32 v13, 0xffff0000, v127
	v_cvt_pk_bf16_f32 v127, v10, v11
	v_fma_f32 v10, v10, s13, v12
	v_fma_f32 v11, v11, s13, v13
	v_readlane_b32 s12, v9, 0
	global_store_dword v4, v127, s[100:101]
	s_add_u32 s100, s100, 0x80000
	s_addc_u32 s101, s101, 0
	global_load_dword v158, v4, s[22:23]
	s_add_u32 s22, s22, 0x80000
	s_addc_u32 s23, s23, 0
	s_waitcnt vmcnt(60)
	v_lshlrev_b32_e32 v12, 16, v128
	v_and_b32_e32 v13, 0xffff0000, v128
	v_cvt_pk_bf16_f32 v128, v10, v11
	v_fma_f32 v10, v10, s12, v12
	v_fma_f32 v11, v11, s12, v13
	v_readlane_b32 s13, v9, 1
	global_store_dword v4, v128, s[100:101]
	s_add_u32 s100, s100, 0x80000
	s_addc_u32 s101, s101, 0
	global_load_dword v159, v4, s[22:23]
	s_add_u32 s22, s22, 0x80000
	s_addc_u32 s23, s23, 0
	s_waitcnt vmcnt(60)
	v_lshlrev_b32_e32 v12, 16, v129
	v_and_b32_e32 v13, 0xffff0000, v129
	v_cvt_pk_bf16_f32 v129, v10, v11
	v_fma_f32 v10, v10, s13, v12
	v_fma_f32 v11, v11, s13, v13
	v_readlane_b32 s12, v9, 2
	global_store_dword v4, v129, s[100:101]
	s_add_u32 s100, s100, 0x80000
	s_addc_u32 s101, s101, 0
	global_load_dword v160, v4, s[22:23]
	s_add_u32 s22, s22, 0x80000
	s_addc_u32 s23, s23, 0
	s_waitcnt vmcnt(60)
	v_lshlrev_b32_e32 v12, 16, v130
	v_and_b32_e32 v13, 0xffff0000, v130
	v_cvt_pk_bf16_f32 v130, v10, v11
	v_fma_f32 v10, v10, s12, v12
	v_fma_f32 v11, v11, s12, v13
	v_readlane_b32 s13, v9, 3
	global_store_dword v4, v130, s[100:101]
	s_add_u32 s100, s100, 0x80000
	s_addc_u32 s101, s101, 0
	global_load_dword v161, v4, s[22:23]
	s_add_u32 s22, s22, 0x80000
	s_addc_u32 s23, s23, 0
	s_waitcnt vmcnt(60)
	v_lshlrev_b32_e32 v12, 16, v131
	v_and_b32_e32 v13, 0xffff0000, v131
	v_cvt_pk_bf16_f32 v131, v10, v11
	v_fma_f32 v10, v10, s13, v12
	v_fma_f32 v11, v11, s13, v13
	v_readlane_b32 s12, v9, 4
	global_store_dword v4, v131, s[100:101]
	s_add_u32 s100, s100, 0x80000
	s_addc_u32 s101, s101, 0
	global_load_dword v162, v4, s[22:23]
	s_add_u32 s22, s22, 0x80000
	s_addc_u32 s23, s23, 0
	s_waitcnt vmcnt(60)
	v_lshlrev_b32_e32 v12, 16, v132
	v_and_b32_e32 v13, 0xffff0000, v132
	v_cvt_pk_bf16_f32 v132, v10, v11
	v_fma_f32 v10, v10, s12, v12
	v_fma_f32 v11, v11, s12, v13
	v_readlane_b32 s13, v9, 5
	global_store_dword v4, v132, s[100:101]
	s_add_u32 s100, s100, 0x80000
	s_addc_u32 s101, s101, 0
	global_load_dword v163, v4, s[22:23]
	s_add_u32 s22, s22, 0x80000
	s_addc_u32 s23, s23, 0
	s_waitcnt vmcnt(60)
	v_lshlrev_b32_e32 v12, 16, v133
	v_and_b32_e32 v13, 0xffff0000, v133
	v_cvt_pk_bf16_f32 v133, v10, v11
	v_fma_f32 v10, v10, s13, v12
	v_fma_f32 v11, v11, s13, v13
	v_readlane_b32 s12, v9, 6
	global_store_dword v4, v133, s[100:101]
	s_add_u32 s100, s100, 0x80000
	s_addc_u32 s101, s101, 0
	global_load_dword v164, v4, s[22:23]
	s_add_u32 s22, s22, 0x80000
	s_addc_u32 s23, s23, 0
	s_waitcnt vmcnt(60)
	v_lshlrev_b32_e32 v12, 16, v134
	v_and_b32_e32 v13, 0xffff0000, v134
	v_cvt_pk_bf16_f32 v134, v10, v11
	v_fma_f32 v10, v10, s12, v12
	v_fma_f32 v11, v11, s12, v13
	v_readlane_b32 s13, v9, 7
	global_store_dword v4, v134, s[100:101]
	s_add_u32 s100, s100, 0x80000
	s_addc_u32 s101, s101, 0
	global_load_dword v165, v4, s[22:23]
	s_add_u32 s22, s22, 0x80000
	s_addc_u32 s23, s23, 0
	s_waitcnt vmcnt(60)
	v_lshlrev_b32_e32 v12, 16, v135
	v_and_b32_e32 v13, 0xffff0000, v135
	v_cvt_pk_bf16_f32 v135, v10, v11
	v_fma_f32 v10, v10, s13, v12
	v_fma_f32 v11, v11, s13, v13
	v_readlane_b32 s12, v9, 8
	global_store_dword v4, v135, s[100:101]
	s_add_u32 s100, s100, 0x80000
	s_addc_u32 s101, s101, 0
	global_load_dword v166, v4, s[22:23]
	s_add_u32 s22, s22, 0x80000
	s_addc_u32 s23, s23, 0
	s_waitcnt vmcnt(60)
	v_lshlrev_b32_e32 v12, 16, v136
	v_and_b32_e32 v13, 0xffff0000, v136
	v_cvt_pk_bf16_f32 v136, v10, v11
	v_fma_f32 v10, v10, s12, v12
	v_fma_f32 v11, v11, s12, v13
	v_readlane_b32 s13, v9, 9
	global_store_dword v4, v136, s[100:101]
	s_add_u32 s100, s100, 0x80000
	s_addc_u32 s101, s101, 0
	global_load_dword v167, v4, s[22:23]
	s_add_u32 s22, s22, 0x80000
	s_addc_u32 s23, s23, 0
	s_waitcnt vmcnt(60)
	v_lshlrev_b32_e32 v12, 16, v137
	v_and_b32_e32 v13, 0xffff0000, v137
	v_cvt_pk_bf16_f32 v137, v10, v11
	v_fma_f32 v10, v10, s13, v12
	v_fma_f32 v11, v11, s13, v13
	v_readlane_b32 s12, v9, 10
	global_store_dword v4, v137, s[100:101]
	s_add_u32 s100, s100, 0x80000
	s_addc_u32 s101, s101, 0
	global_load_dword v168, v4, s[22:23]
	s_add_u32 s22, s22, 0x80000
	s_addc_u32 s23, s23, 0
	s_waitcnt vmcnt(60)
	v_lshlrev_b32_e32 v12, 16, v138
	v_and_b32_e32 v13, 0xffff0000, v138
	v_cvt_pk_bf16_f32 v138, v10, v11
	v_fma_f32 v10, v10, s12, v12
	v_fma_f32 v11, v11, s12, v13
	v_readlane_b32 s13, v9, 11
	global_store_dword v4, v138, s[100:101]
	s_add_u32 s100, s100, 0x80000
	s_addc_u32 s101, s101, 0
	global_load_dword v169, v4, s[22:23]
	s_add_u32 s22, s22, 0x80000
	s_addc_u32 s23, s23, 0
	s_waitcnt vmcnt(60)
	v_lshlrev_b32_e32 v12, 16, v139
	v_and_b32_e32 v13, 0xffff0000, v139
	v_cvt_pk_bf16_f32 v139, v10, v11
	v_fma_f32 v10, v10, s13, v12
	v_fma_f32 v11, v11, s13, v13
	v_readlane_b32 s12, v9, 12
	global_store_dword v4, v139, s[100:101]
	s_add_u32 s100, s100, 0x80000
	s_addc_u32 s101, s101, 0
	global_load_dword v170, v4, s[22:23]
	s_add_u32 s22, s22, 0x80000
	s_addc_u32 s23, s23, 0
	s_waitcnt vmcnt(60)
	v_lshlrev_b32_e32 v12, 16, v140
	v_and_b32_e32 v13, 0xffff0000, v140
	v_cvt_pk_bf16_f32 v140, v10, v11
	v_fma_f32 v10, v10, s12, v12
	v_fma_f32 v11, v11, s12, v13
	v_readlane_b32 s13, v9, 13
	global_store_dword v4, v140, s[100:101]
	s_add_u32 s100, s100, 0x80000
	s_addc_u32 s101, s101, 0
	global_load_dword v171, v4, s[22:23]
	s_add_u32 s22, s22, 0x80000
	s_addc_u32 s23, s23, 0
	s_waitcnt vmcnt(60)
	v_lshlrev_b32_e32 v12, 16, v141
	v_and_b32_e32 v13, 0xffff0000, v141
	v_cvt_pk_bf16_f32 v141, v10, v11
	v_fma_f32 v10, v10, s13, v12
	v_fma_f32 v11, v11, s13, v13
	v_readlane_b32 s12, v9, 14
	global_store_dword v4, v141, s[100:101]
	s_add_u32 s100, s100, 0x80000
	s_addc_u32 s101, s101, 0
	global_load_dword v172, v4, s[22:23]
	s_add_u32 s22, s22, 0x80000
	s_addc_u32 s23, s23, 0
	s_waitcnt vmcnt(60)
	v_lshlrev_b32_e32 v12, 16, v142
	v_and_b32_e32 v13, 0xffff0000, v142
	v_cvt_pk_bf16_f32 v142, v10, v11
	v_fma_f32 v10, v10, s12, v12
	v_fma_f32 v11, v11, s12, v13
	v_readlane_b32 s13, v9, 15
	global_store_dword v4, v142, s[100:101]
	s_add_u32 s100, s100, 0x80000
	s_addc_u32 s101, s101, 0
	global_load_dword v173, v4, s[22:23]
	s_add_u32 s22, s22, 0x80000
	s_addc_u32 s23, s23, 0
	s_waitcnt vmcnt(60)
	v_lshlrev_b32_e32 v12, 16, v143
	v_and_b32_e32 v13, 0xffff0000, v143
	v_cvt_pk_bf16_f32 v143, v10, v11
	v_fma_f32 v10, v10, s13, v12
	v_fma_f32 v11, v11, s13, v13
	v_readlane_b32 s12, v9, 16
	global_store_dword v4, v143, s[100:101]
	s_add_u32 s100, s100, 0x80000
	s_addc_u32 s101, s101, 0
	global_load_dword v174, v4, s[22:23]
	s_add_u32 s22, s22, 0x80000
	s_addc_u32 s23, s23, 0
	s_waitcnt vmcnt(60)
	v_lshlrev_b32_e32 v12, 16, v144
	v_and_b32_e32 v13, 0xffff0000, v144
	v_cvt_pk_bf16_f32 v144, v10, v11
	v_fma_f32 v10, v10, s12, v12
	v_fma_f32 v11, v11, s12, v13
	v_readlane_b32 s13, v9, 17
	global_store_dword v4, v144, s[100:101]
	s_add_u32 s100, s100, 0x80000
	s_addc_u32 s101, s101, 0
	global_load_dword v175, v4, s[22:23]
	s_add_u32 s22, s22, 0x80000
	s_addc_u32 s23, s23, 0
	s_waitcnt vmcnt(60)
	v_lshlrev_b32_e32 v12, 16, v145
	v_and_b32_e32 v13, 0xffff0000, v145
	v_cvt_pk_bf16_f32 v145, v10, v11
	v_fma_f32 v10, v10, s13, v12
	v_fma_f32 v11, v11, s13, v13
	v_readlane_b32 s12, v9, 18
	global_store_dword v4, v145, s[100:101]
	s_add_u32 s100, s100, 0x80000
	s_addc_u32 s101, s101, 0
	global_load_dword v176, v4, s[22:23]
	s_add_u32 s22, s22, 0x80000
	s_addc_u32 s23, s23, 0
	s_waitcnt vmcnt(60)
	v_lshlrev_b32_e32 v12, 16, v146
	v_and_b32_e32 v13, 0xffff0000, v146
	v_cvt_pk_bf16_f32 v146, v10, v11
	v_fma_f32 v10, v10, s12, v12
	v_fma_f32 v11, v11, s12, v13
	v_readlane_b32 s13, v9, 19
	global_store_dword v4, v146, s[100:101]
	s_add_u32 s100, s100, 0x80000
	s_addc_u32 s101, s101, 0
	global_load_dword v177, v4, s[22:23]
	s_add_u32 s22, s22, 0x80000
	s_addc_u32 s23, s23, 0
	s_waitcnt vmcnt(60)
	v_lshlrev_b32_e32 v12, 16, v147
	v_and_b32_e32 v13, 0xffff0000, v147
	v_cvt_pk_bf16_f32 v147, v10, v11
	v_fma_f32 v10, v10, s13, v12
	v_fma_f32 v11, v11, s13, v13
	v_readlane_b32 s12, v9, 20
	global_store_dword v4, v147, s[100:101]
	s_add_u32 s100, s100, 0x80000
	s_addc_u32 s101, s101, 0
	global_load_dword v178, v4, s[22:23]
	s_add_u32 s22, s22, 0x80000
	s_addc_u32 s23, s23, 0
	s_waitcnt vmcnt(60)
	v_lshlrev_b32_e32 v12, 16, v148
	v_and_b32_e32 v13, 0xffff0000, v148
	v_cvt_pk_bf16_f32 v148, v10, v11
	v_fma_f32 v10, v10, s12, v12
	v_fma_f32 v11, v11, s12, v13
	v_readlane_b32 s13, v9, 21
	global_store_dword v4, v148, s[100:101]
	s_add_u32 s100, s100, 0x80000
	s_addc_u32 s101, s101, 0
	global_load_dword v179, v4, s[22:23]
	s_add_u32 s22, s22, 0x80000
	s_addc_u32 s23, s23, 0
	s_waitcnt vmcnt(60)
	v_lshlrev_b32_e32 v12, 16, v149
	v_and_b32_e32 v13, 0xffff0000, v149
	v_cvt_pk_bf16_f32 v149, v10, v11
	v_fma_f32 v10, v10, s13, v12
	v_fma_f32 v11, v11, s13, v13
	v_readlane_b32 s12, v9, 22
	global_store_dword v4, v149, s[100:101]
	s_add_u32 s100, s100, 0x80000
	s_addc_u32 s101, s101, 0
	global_load_dword v180, v4, s[22:23]
	s_add_u32 s22, s22, 0x80000
	s_addc_u32 s23, s23, 0
	s_waitcnt vmcnt(60)
	v_lshlrev_b32_e32 v12, 16, v150
	v_and_b32_e32 v13, 0xffff0000, v150
	v_cvt_pk_bf16_f32 v150, v10, v11
	v_fma_f32 v10, v10, s12, v12
	v_fma_f32 v11, v11, s12, v13
	v_readlane_b32 s13, v9, 23
	global_store_dword v4, v150, s[100:101]
	s_add_u32 s100, s100, 0x80000
	s_addc_u32 s101, s101, 0
	global_load_dword v181, v4, s[22:23]
	s_add_u32 s22, s22, 0x80000
	s_addc_u32 s23, s23, 0
	s_waitcnt vmcnt(60)
	v_lshlrev_b32_e32 v12, 16, v151
	v_and_b32_e32 v13, 0xffff0000, v151
	v_cvt_pk_bf16_f32 v151, v10, v11
	v_fma_f32 v10, v10, s13, v12
	v_fma_f32 v11, v11, s13, v13
	v_readlane_b32 s12, v9, 24
	global_store_dword v4, v151, s[100:101]
	s_add_u32 s100, s100, 0x80000
	s_addc_u32 s101, s101, 0
	global_load_dword v182, v4, s[22:23]
	s_add_u32 s22, s22, 0x80000
	s_addc_u32 s23, s23, 0
	s_waitcnt vmcnt(60)
	v_lshlrev_b32_e32 v12, 16, v152
	v_and_b32_e32 v13, 0xffff0000, v152
	v_cvt_pk_bf16_f32 v152, v10, v11
	v_fma_f32 v10, v10, s12, v12
	v_fma_f32 v11, v11, s12, v13
	v_readlane_b32 s13, v9, 25
	global_store_dword v4, v152, s[100:101]
	s_add_u32 s100, s100, 0x80000
	s_addc_u32 s101, s101, 0
	global_load_dword v183, v4, s[22:23]
	s_add_u32 s22, s22, 0x80000
	s_addc_u32 s23, s23, 0
	s_waitcnt vmcnt(60)
	v_lshlrev_b32_e32 v12, 16, v153
	v_and_b32_e32 v13, 0xffff0000, v153
	v_cvt_pk_bf16_f32 v153, v10, v11
	v_fma_f32 v10, v10, s13, v12
	v_fma_f32 v11, v11, s13, v13
	v_readlane_b32 s12, v9, 26
	global_store_dword v4, v153, s[100:101]
	s_add_u32 s100, s100, 0x80000
	s_addc_u32 s101, s101, 0
	global_load_dword v184, v4, s[22:23]
	s_add_u32 s22, s22, 0x80000
	s_addc_u32 s23, s23, 0
	s_waitcnt vmcnt(60)
	v_lshlrev_b32_e32 v12, 16, v154
	v_and_b32_e32 v13, 0xffff0000, v154
	v_cvt_pk_bf16_f32 v154, v10, v11
	v_fma_f32 v10, v10, s12, v12
	v_fma_f32 v11, v11, s12, v13
	v_readlane_b32 s13, v9, 27
	global_store_dword v4, v154, s[100:101]
	s_add_u32 s100, s100, 0x80000
	s_addc_u32 s101, s101, 0
	global_load_dword v185, v4, s[22:23]
	s_add_u32 s22, s22, 0x80000
	s_addc_u32 s23, s23, 0
	s_waitcnt vmcnt(60)
	v_lshlrev_b32_e32 v12, 16, v155
	v_and_b32_e32 v13, 0xffff0000, v155
	v_cvt_pk_bf16_f32 v155, v10, v11
	v_fma_f32 v10, v10, s13, v12
	v_fma_f32 v11, v11, s13, v13
	v_readlane_b32 s12, v9, 28
	global_store_dword v4, v155, s[100:101]
	s_add_u32 s100, s100, 0x80000
	s_addc_u32 s101, s101, 0
	global_load_dword v186, v4, s[22:23]
	s_add_u32 s22, s22, 0x80000
	s_addc_u32 s23, s23, 0
	s_waitcnt vmcnt(60)
	v_lshlrev_b32_e32 v12, 16, v156
	v_and_b32_e32 v13, 0xffff0000, v156
	v_cvt_pk_bf16_f32 v156, v10, v11
	v_fma_f32 v10, v10, s12, v12
	v_fma_f32 v11, v11, s12, v13
	v_readlane_b32 s13, v9, 29
	global_store_dword v4, v156, s[100:101]
	s_add_u32 s100, s100, 0x80000
	s_addc_u32 s101, s101, 0
	global_load_dword v187, v4, s[22:23]
	s_add_u32 s22, s22, 0x80000
	s_addc_u32 s23, s23, 0
	s_waitcnt vmcnt(60)
	v_lshlrev_b32_e32 v12, 16, v157
	v_and_b32_e32 v13, 0xffff0000, v157
	v_cvt_pk_bf16_f32 v157, v10, v11
	v_fma_f32 v10, v10, s13, v12
	v_fma_f32 v11, v11, s13, v13
	v_readlane_b32 s12, v9, 30
	global_store_dword v4, v157, s[100:101]
	s_add_u32 s100, s100, 0x80000
	s_addc_u32 s101, s101, 0
	global_load_dword v188, v4, s[22:23]
	s_add_u32 s22, s22, 0x80000
	s_addc_u32 s23, s23, 0
	s_waitcnt vmcnt(60)
	v_lshlrev_b32_e32 v12, 16, v158
	v_and_b32_e32 v13, 0xffff0000, v158
	v_cvt_pk_bf16_f32 v158, v10, v11
	v_fma_f32 v10, v10, s12, v12
	v_fma_f32 v11, v11, s12, v13
	v_readlane_b32 s13, v9, 31
	global_store_dword v4, v158, s[100:101]
	s_add_u32 s100, s100, 0x80000
	s_addc_u32 s101, s101, 0
	global_load_dword v189, v4, s[22:23]
	s_add_u32 s22, s22, 0x80000
	s_addc_u32 s23, s23, 0
	s_waitcnt vmcnt(60)
	v_lshlrev_b32_e32 v12, 16, v159
	v_and_b32_e32 v13, 0xffff0000, v159
	v_cvt_pk_bf16_f32 v159, v10, v11
	v_fma_f32 v10, v10, s13, v12
	v_fma_f32 v11, v11, s13, v13
	v_readlane_b32 s12, v9, 32
	global_store_dword v4, v159, s[100:101]
	s_add_u32 s100, s100, 0x80000
	s_addc_u32 s101, s101, 0
	global_load_dword v190, v4, s[22:23]
	s_add_u32 s22, s22, 0x80000
	s_addc_u32 s23, s23, 0
	s_waitcnt vmcnt(60)
	v_lshlrev_b32_e32 v12, 16, v160
	v_and_b32_e32 v13, 0xffff0000, v160
	v_cvt_pk_bf16_f32 v160, v10, v11
	v_fma_f32 v10, v10, s12, v12
	v_fma_f32 v11, v11, s12, v13
	v_readlane_b32 s13, v9, 33
	global_store_dword v4, v160, s[100:101]
	s_add_u32 s100, s100, 0x80000
	s_addc_u32 s101, s101, 0
	global_load_dword v191, v4, s[22:23]
	s_add_u32 s22, s22, 0x80000
	s_addc_u32 s23, s23, 0
	s_waitcnt vmcnt(60)
	v_lshlrev_b32_e32 v12, 16, v161
	v_and_b32_e32 v13, 0xffff0000, v161
	v_cvt_pk_bf16_f32 v161, v10, v11
	v_fma_f32 v10, v10, s13, v12
	v_fma_f32 v11, v11, s13, v13
	v_readlane_b32 s12, v9, 34
	global_store_dword v4, v161, s[100:101]
	s_add_u32 s100, s100, 0x80000
	s_addc_u32 s101, s101, 0
	s_waitcnt vmcnt(59)
	v_lshlrev_b32_e32 v12, 16, v162
	v_and_b32_e32 v13, 0xffff0000, v162
	v_cvt_pk_bf16_f32 v162, v10, v11
	v_fma_f32 v10, v10, s12, v12
	v_fma_f32 v11, v11, s12, v13
	v_readlane_b32 s13, v9, 35
	global_store_dword v4, v162, s[100:101]
	s_add_u32 s100, s100, 0x80000
	s_addc_u32 s101, s101, 0
	s_waitcnt vmcnt(58)
	v_lshlrev_b32_e32 v12, 16, v163
	v_and_b32_e32 v13, 0xffff0000, v163
	v_cvt_pk_bf16_f32 v163, v10, v11
	v_fma_f32 v10, v10, s13, v12
	v_fma_f32 v11, v11, s13, v13
	v_readlane_b32 s12, v9, 36
	global_store_dword v4, v163, s[100:101]
	s_add_u32 s100, s100, 0x80000
	s_addc_u32 s101, s101, 0
	s_waitcnt vmcnt(57)
	v_lshlrev_b32_e32 v12, 16, v164
	v_and_b32_e32 v13, 0xffff0000, v164
	v_cvt_pk_bf16_f32 v164, v10, v11
	v_fma_f32 v10, v10, s12, v12
	v_fma_f32 v11, v11, s12, v13
	v_readlane_b32 s13, v9, 37
	global_store_dword v4, v164, s[100:101]
	s_add_u32 s100, s100, 0x80000
	s_addc_u32 s101, s101, 0
	s_waitcnt vmcnt(56)
	v_lshlrev_b32_e32 v12, 16, v165
	v_and_b32_e32 v13, 0xffff0000, v165
	v_cvt_pk_bf16_f32 v165, v10, v11
	v_fma_f32 v10, v10, s13, v12
	v_fma_f32 v11, v11, s13, v13
	v_readlane_b32 s12, v9, 38
	global_store_dword v4, v165, s[100:101]
	s_add_u32 s100, s100, 0x80000
	s_addc_u32 s101, s101, 0
	s_waitcnt vmcnt(55)
	v_lshlrev_b32_e32 v12, 16, v166
	v_and_b32_e32 v13, 0xffff0000, v166
	v_cvt_pk_bf16_f32 v166, v10, v11
	v_fma_f32 v10, v10, s12, v12
	v_fma_f32 v11, v11, s12, v13
	v_readlane_b32 s13, v9, 39
	global_store_dword v4, v166, s[100:101]
	s_add_u32 s100, s100, 0x80000
	s_addc_u32 s101, s101, 0
	s_waitcnt vmcnt(54)
	v_lshlrev_b32_e32 v12, 16, v167
	v_and_b32_e32 v13, 0xffff0000, v167
	v_cvt_pk_bf16_f32 v167, v10, v11
	v_fma_f32 v10, v10, s13, v12
	v_fma_f32 v11, v11, s13, v13
	v_readlane_b32 s12, v9, 40
	global_store_dword v4, v167, s[100:101]
	s_add_u32 s100, s100, 0x80000
	s_addc_u32 s101, s101, 0
	s_waitcnt vmcnt(53)
	v_lshlrev_b32_e32 v12, 16, v168
	v_and_b32_e32 v13, 0xffff0000, v168
	v_cvt_pk_bf16_f32 v168, v10, v11
	v_fma_f32 v10, v10, s12, v12
	v_fma_f32 v11, v11, s12, v13
	v_readlane_b32 s13, v9, 41
	global_store_dword v4, v168, s[100:101]
	s_add_u32 s100, s100, 0x80000
	s_addc_u32 s101, s101, 0
	s_waitcnt vmcnt(52)
	v_lshlrev_b32_e32 v12, 16, v169
	v_and_b32_e32 v13, 0xffff0000, v169
	v_cvt_pk_bf16_f32 v169, v10, v11
	v_fma_f32 v10, v10, s13, v12
	v_fma_f32 v11, v11, s13, v13
	v_readlane_b32 s12, v9, 42
	global_store_dword v4, v169, s[100:101]
	s_add_u32 s100, s100, 0x80000
	s_addc_u32 s101, s101, 0
	s_waitcnt vmcnt(51)
	v_lshlrev_b32_e32 v12, 16, v170
	v_and_b32_e32 v13, 0xffff0000, v170
	v_cvt_pk_bf16_f32 v170, v10, v11
	v_fma_f32 v10, v10, s12, v12
	v_fma_f32 v11, v11, s12, v13
	v_readlane_b32 s13, v9, 43
	global_store_dword v4, v170, s[100:101]
	s_add_u32 s100, s100, 0x80000
	s_addc_u32 s101, s101, 0
	s_waitcnt vmcnt(50)
	v_lshlrev_b32_e32 v12, 16, v171
	v_and_b32_e32 v13, 0xffff0000, v171
	v_cvt_pk_bf16_f32 v171, v10, v11
	v_fma_f32 v10, v10, s13, v12
	v_fma_f32 v11, v11, s13, v13
	v_readlane_b32 s12, v9, 44
	global_store_dword v4, v171, s[100:101]
	s_add_u32 s100, s100, 0x80000
	s_addc_u32 s101, s101, 0
	s_waitcnt vmcnt(49)
	v_lshlrev_b32_e32 v12, 16, v172
	v_and_b32_e32 v13, 0xffff0000, v172
	v_cvt_pk_bf16_f32 v172, v10, v11
	v_fma_f32 v10, v10, s12, v12
	v_fma_f32 v11, v11, s12, v13
	v_readlane_b32 s13, v9, 45
	global_store_dword v4, v172, s[100:101]
	s_add_u32 s100, s100, 0x80000
	s_addc_u32 s101, s101, 0
	s_waitcnt vmcnt(48)
	v_lshlrev_b32_e32 v12, 16, v173
	v_and_b32_e32 v13, 0xffff0000, v173
	v_cvt_pk_bf16_f32 v173, v10, v11
	v_fma_f32 v10, v10, s13, v12
	v_fma_f32 v11, v11, s13, v13
	v_readlane_b32 s12, v9, 46
	global_store_dword v4, v173, s[100:101]
	s_add_u32 s100, s100, 0x80000
	s_addc_u32 s101, s101, 0
	s_waitcnt vmcnt(47)
	v_lshlrev_b32_e32 v12, 16, v174
	v_and_b32_e32 v13, 0xffff0000, v174
	v_cvt_pk_bf16_f32 v174, v10, v11
	v_fma_f32 v10, v10, s12, v12
	v_fma_f32 v11, v11, s12, v13
	v_readlane_b32 s13, v9, 47
	global_store_dword v4, v174, s[100:101]
	s_add_u32 s100, s100, 0x80000
	s_addc_u32 s101, s101, 0
	s_waitcnt vmcnt(46)
	v_lshlrev_b32_e32 v12, 16, v175
	v_and_b32_e32 v13, 0xffff0000, v175
	v_cvt_pk_bf16_f32 v175, v10, v11
	v_fma_f32 v10, v10, s13, v12
	v_fma_f32 v11, v11, s13, v13
	v_readlane_b32 s12, v9, 48
	global_store_dword v4, v175, s[100:101]
	s_add_u32 s100, s100, 0x80000
	s_addc_u32 s101, s101, 0
	s_waitcnt vmcnt(45)
	v_lshlrev_b32_e32 v12, 16, v176
	v_and_b32_e32 v13, 0xffff0000, v176
	v_cvt_pk_bf16_f32 v176, v10, v11
	v_fma_f32 v10, v10, s12, v12
	v_fma_f32 v11, v11, s12, v13
	v_readlane_b32 s13, v9, 49
	global_store_dword v4, v176, s[100:101]
	s_add_u32 s100, s100, 0x80000
	s_addc_u32 s101, s101, 0
	s_waitcnt vmcnt(44)
	v_lshlrev_b32_e32 v12, 16, v177
	v_and_b32_e32 v13, 0xffff0000, v177
	v_cvt_pk_bf16_f32 v177, v10, v11
	v_fma_f32 v10, v10, s13, v12
	v_fma_f32 v11, v11, s13, v13
	v_readlane_b32 s12, v9, 50
	global_store_dword v4, v177, s[100:101]
	s_add_u32 s100, s100, 0x80000
	s_addc_u32 s101, s101, 0
	s_waitcnt vmcnt(43)
	v_lshlrev_b32_e32 v12, 16, v178
	v_and_b32_e32 v13, 0xffff0000, v178
	v_cvt_pk_bf16_f32 v178, v10, v11
	v_fma_f32 v10, v10, s12, v12
	v_fma_f32 v11, v11, s12, v13
	v_readlane_b32 s13, v9, 51
	global_store_dword v4, v178, s[100:101]
	s_add_u32 s100, s100, 0x80000
	s_addc_u32 s101, s101, 0
	s_waitcnt vmcnt(42)
	v_lshlrev_b32_e32 v12, 16, v179
	v_and_b32_e32 v13, 0xffff0000, v179
	v_cvt_pk_bf16_f32 v179, v10, v11
	v_fma_f32 v10, v10, s13, v12
	v_fma_f32 v11, v11, s13, v13
	v_readlane_b32 s12, v9, 52
	global_store_dword v4, v179, s[100:101]
	s_add_u32 s100, s100, 0x80000
	s_addc_u32 s101, s101, 0
	s_waitcnt vmcnt(41)
	v_lshlrev_b32_e32 v12, 16, v180
	v_and_b32_e32 v13, 0xffff0000, v180
	v_cvt_pk_bf16_f32 v180, v10, v11
	v_fma_f32 v10, v10, s12, v12
	v_fma_f32 v11, v11, s12, v13
	v_readlane_b32 s13, v9, 53
	global_store_dword v4, v180, s[100:101]
	s_add_u32 s100, s100, 0x80000
	s_addc_u32 s101, s101, 0
	s_waitcnt vmcnt(40)
	v_lshlrev_b32_e32 v12, 16, v181
	v_and_b32_e32 v13, 0xffff0000, v181
	v_cvt_pk_bf16_f32 v181, v10, v11
	v_fma_f32 v10, v10, s13, v12
	v_fma_f32 v11, v11, s13, v13
	v_readlane_b32 s12, v9, 54
	global_store_dword v4, v181, s[100:101]
	s_add_u32 s100, s100, 0x80000
	s_addc_u32 s101, s101, 0
	s_waitcnt vmcnt(39)
	v_lshlrev_b32_e32 v12, 16, v182
	v_and_b32_e32 v13, 0xffff0000, v182
	v_cvt_pk_bf16_f32 v182, v10, v11
	v_fma_f32 v10, v10, s12, v12
	v_fma_f32 v11, v11, s12, v13
	v_readlane_b32 s13, v9, 55
	global_store_dword v4, v182, s[100:101]
	s_add_u32 s100, s100, 0x80000
	s_addc_u32 s101, s101, 0
	s_waitcnt vmcnt(38)
	v_lshlrev_b32_e32 v12, 16, v183
	v_and_b32_e32 v13, 0xffff0000, v183
	v_cvt_pk_bf16_f32 v183, v10, v11
	v_fma_f32 v10, v10, s13, v12
	v_fma_f32 v11, v11, s13, v13
	v_readlane_b32 s12, v9, 56
	global_store_dword v4, v183, s[100:101]
	s_add_u32 s100, s100, 0x80000
	s_addc_u32 s101, s101, 0
	s_waitcnt vmcnt(37)
	v_lshlrev_b32_e32 v12, 16, v184
	v_and_b32_e32 v13, 0xffff0000, v184
	v_cvt_pk_bf16_f32 v184, v10, v11
	v_fma_f32 v10, v10, s12, v12
	v_fma_f32 v11, v11, s12, v13
	v_readlane_b32 s13, v9, 57
	global_store_dword v4, v184, s[100:101]
	s_add_u32 s100, s100, 0x80000
	s_addc_u32 s101, s101, 0
	s_waitcnt vmcnt(36)
	v_lshlrev_b32_e32 v12, 16, v185
	v_and_b32_e32 v13, 0xffff0000, v185
	v_cvt_pk_bf16_f32 v185, v10, v11
	v_fma_f32 v10, v10, s13, v12
	v_fma_f32 v11, v11, s13, v13
	v_readlane_b32 s12, v9, 58
	global_store_dword v4, v185, s[100:101]
	s_add_u32 s100, s100, 0x80000
	s_addc_u32 s101, s101, 0
	s_waitcnt vmcnt(35)
	v_lshlrev_b32_e32 v12, 16, v186
	v_and_b32_e32 v13, 0xffff0000, v186
	v_cvt_pk_bf16_f32 v186, v10, v11
	v_fma_f32 v10, v10, s12, v12
	v_fma_f32 v11, v11, s12, v13
	v_readlane_b32 s13, v9, 59
	global_store_dword v4, v186, s[100:101]
	s_add_u32 s100, s100, 0x80000
	s_addc_u32 s101, s101, 0
	s_waitcnt vmcnt(34)
	v_lshlrev_b32_e32 v12, 16, v187
	v_and_b32_e32 v13, 0xffff0000, v187
	v_cvt_pk_bf16_f32 v187, v10, v11
	v_fma_f32 v10, v10, s13, v12
	v_fma_f32 v11, v11, s13, v13
	v_readlane_b32 s12, v9, 60
	global_store_dword v4, v187, s[100:101]
	s_add_u32 s100, s100, 0x80000
	s_addc_u32 s101, s101, 0
	s_waitcnt vmcnt(33)
	v_lshlrev_b32_e32 v12, 16, v188
	v_and_b32_e32 v13, 0xffff0000, v188
	v_cvt_pk_bf16_f32 v188, v10, v11
	v_fma_f32 v10, v10, s12, v12
	v_fma_f32 v11, v11, s12, v13
	v_readlane_b32 s13, v9, 61
	global_store_dword v4, v188, s[100:101]
	s_add_u32 s100, s100, 0x80000
	s_addc_u32 s101, s101, 0
	s_waitcnt vmcnt(32)
	v_lshlrev_b32_e32 v12, 16, v189
	v_and_b32_e32 v13, 0xffff0000, v189
	v_cvt_pk_bf16_f32 v189, v10, v11
	v_fma_f32 v10, v10, s13, v12
	v_fma_f32 v11, v11, s13, v13
	v_readlane_b32 s12, v9, 62
	global_store_dword v4, v189, s[100:101]
	s_add_u32 s100, s100, 0x80000
	s_addc_u32 s101, s101, 0
	s_waitcnt vmcnt(31)
	v_lshlrev_b32_e32 v12, 16, v190
	v_and_b32_e32 v13, 0xffff0000, v190
	v_cvt_pk_bf16_f32 v190, v10, v11
	v_fma_f32 v10, v10, s12, v12
	v_fma_f32 v11, v11, s12, v13
	v_readlane_b32 s13, v9, 63
	global_store_dword v4, v190, s[100:101]
	s_add_u32 s100, s100, 0x80000
	s_addc_u32 s101, s101, 0
	s_waitcnt vmcnt(30)
	v_lshlrev_b32_e32 v12, 16, v191
	v_and_b32_e32 v13, 0xffff0000, v191
	v_cvt_pk_bf16_f32 v191, v10, v11
	v_fma_f32 v10, v10, s13, v12
	v_fma_f32 v11, v11, s13, v13
	global_store_dword v4, v191, s[100:101]
	s_add_u32 s100, s100, 0x80000
	s_addc_u32 s101, s101, 0
	v_add_u32_e32 v2, s30, v2
	s_mov_b32 s12, 0x1ffff
	v_cmp_lt_i32_e32 vcc, s12, v2
	v_readlane_b32 s12, v244, 13
	v_readlane_b32 s13, v244, 14
	s_or_b64 s[20:21], vcc, s[20:21]
	s_nop 0
	v_lshl_add_u64 v[4:5], v[4:5], 0, s[12:13]
	s_andn2_b64 exec, exec, s[20:21]
	s_cbranch_execnz .LBB0_42

.LBB0_249:
	v_mov_b32_e32 v1, v220
	s_movk_i32 s12, 0x100
	s_nop 0
	v_cmp_gt_i32_e32 vcc, s12, v1
	s_and_saveexec_b64 s[16:17], vcc
	s_cbranch_execz .LBB0_251
	v_lshl_add_u32 v2, s46, 8, v1
	v_lshlrev_b32_e32 v2, 2, v2
	v_lshl_add_u32 v1, v1, 2, 0
	v_add_u32_e32 v1, 0x20000, v1
	global_load_dword v4, v2, s[0:1]
	v_add_u32_e32 v3, 0x8000, v2
	global_load_dword v5, v3, s[0:1]
	v_add_u32_e32 v12, 0x10000, v2
	global_load_dword v6, v12, s[0:1]
	v_add_u32_e32 v13, 0x18000, v2
	global_load_dword v7, v13, s[0:1]
	v_add_u32_e32 v14, 0x20000, v2
	global_load_dword v8, v14, s[0:1]
	v_add_u32_e32 v15, 0x28000, v2
	global_load_dword v9, v15, s[0:1]
	v_add_u32_e32 v16, 0x30000, v2
	global_load_dword v10, v16, s[0:1]
	v_add_u32_e32 v17, 0x38000, v2
	global_load_dword v11, v17, s[0:1]
	s_waitcnt vmcnt(7)
	v_add_f32_e32 v2, 0, v4
	s_waitcnt vmcnt(6)
	v_add_f32_e32 v2, v2, v5
	s_waitcnt vmcnt(5)
	v_add_f32_e32 v2, v2, v6
	s_waitcnt vmcnt(4)
	v_add_f32_e32 v2, v2, v7
	s_waitcnt vmcnt(3)
	v_add_f32_e32 v2, v2, v8
	s_waitcnt vmcnt(2)
	v_add_f32_e32 v2, v2, v9
	s_waitcnt vmcnt(1)
	v_add_f32_e32 v2, v2, v10
	s_waitcnt vmcnt(0)
	v_add_f32_e32 v2, v2, v11
	v_fmamk_f32 v2, v2, 0x3a000000, v223
	v_cmp_gt_f32_e32 vcc, s4, v2
	v_mul_f32_e32 v3, 0x4b800000, v2
	s_nop 0
	v_cndmask_b32_e32 v2, v2, v3, vcc
	v_rsq_f32_e32 v2, v2
	s_nop 0
	v_mul_f32_e32 v3, 0x45800000, v2
	v_cndmask_b32_e32 v2, v2, v3, vcc
	ds_write_b32 v1, v2

	.amdhsa_kernel _Z10hybrid_fwd4Args
		.amdhsa_group_segment_fixed_size 0
		.amdhsa_private_segment_fixed_size 0
		.amdhsa_kernarg_size 368
		.amdhsa_user_sgpr_count 2
		.amdhsa_user_sgpr_dispatch_ptr 0
		.amdhsa_user_sgpr_queue_ptr 0
		.amdhsa_user_sgpr_kernarg_segment_ptr 1
		.amdhsa_user_sgpr_dispatch_id 0
		.amdhsa_user_sgpr_kernarg_preload_length 0
		.amdhsa_user_sgpr_kernarg_preload_offset 0
		.amdhsa_user_sgpr_private_segment_size 0
		.amdhsa_uses_dynamic_stack 0
		.amdhsa_enable_private_segment 0
		.amdhsa_system_sgpr_workgroup_id_x 1
		.amdhsa_system_sgpr_workgroup_id_y 0
		.amdhsa_system_sgpr_workgroup_id_z 0
		.amdhsa_system_sgpr_workgroup_info 0
		.amdhsa_system_vgpr_workitem_id 2
		.amdhsa_next_free_vgpr 247
		.amdhsa_next_free_sgpr 102
		.amdhsa_accum_offset 248
		.amdhsa_reserve_vcc 1
		.amdhsa_float_round_mode_32 0
		.amdhsa_float_round_mode_16_64 0
		.amdhsa_float_denorm_mode_32 3
		.amdhsa_float_denorm_mode_16_64 3
		.amdhsa_dx10_clamp 1
		.amdhsa_ieee_mode 1
		.amdhsa_fp16_overflow 0
		.amdhsa_tg_split 0
		.amdhsa_exception_fp_ieee_invalid_op 0
		.amdhsa_exception_fp_denorm_src 0
		.amdhsa_exception_fp_ieee_div_zero 0
		.amdhsa_exception_fp_ieee_overflow 0
		.amdhsa_exception_fp_ieee_underflow 0
		.amdhsa_exception_fp_ieee_inexact 0
		.amdhsa_exception_int_div_zero 0
	.end_amdhsa_kernel

.Lfunc_end0:
	.size	_Z10hybrid_fwd4Args, .Lfunc_end0-_Z10hybrid_fwd4Args
	.set _Z10hybrid_fwd4Args.num_vgpr, 247
	.set _Z10hybrid_fwd4Args.num_agpr, 0
	.set _Z10hybrid_fwd4Args.numbered_sgpr, 102
	.set _Z10hybrid_fwd4Args.num_named_barrier, 0
	.set _Z10hybrid_fwd4Args.private_seg_size, 0
	.set _Z10hybrid_fwd4Args.uses_vcc, 1
	.set _Z10hybrid_fwd4Args.uses_flat_scratch, 0
	.set _Z10hybrid_fwd4Args.has_dyn_sized_stack, 0
	.set _Z10hybrid_fwd4Args.has_recursion, 0
	.set _Z10hybrid_fwd4Args.has_indirect_call, 0

amdhsa.kernels:
  - .agpr_count:     0
    .args:
      - .offset:         0
        .size:           112
        .value_kind:     by_value
      - .offset:         112
        .size:           4
        .value_kind:     hidden_block_count_x
      - .offset:         116
        .size:           4
        .value_kind:     hidden_block_count_y
      - .offset:         120
        .size:           4
        .value_kind:     hidden_block_count_z
      - .offset:         124
        .size:           2
        .value_kind:     hidden_group_size_x
      - .offset:         126
        .size:           2
        .value_kind:     hidden_group_size_y
      - .offset:         128
        .size:           2
        .value_kind:     hidden_group_size_z
      - .offset:         130
        .size:           2
        .value_kind:     hidden_remainder_x
      - .offset:         132
        .size:           2
        .value_kind:     hidden_remainder_y
      - .offset:         134
        .size:           2
        .value_kind:     hidden_remainder_z
      - .offset:         152
        .size:           8
        .value_kind:     hidden_global_offset_x
      - .offset:         160
        .size:           8
        .value_kind:     hidden_global_offset_y
      - .offset:         168
        .size:           8
        .value_kind:     hidden_global_offset_z
      - .offset:         176
        .size:           2
        .value_kind:     hidden_grid_dims
      - .offset:         200
        .size:           8
        .value_kind:     hidden_multigrid_sync_arg
      - .offset:         232
        .size:           4
        .value_kind:     hidden_dynamic_lds_size
    .group_segment_fixed_size: 0
    .kernarg_segment_align: 8
    .kernarg_segment_size: 368
    .language:       OpenCL C
    .language_version:
      - 2
      - 0
    .max_flat_workgroup_size: 512
    .name:           _Z10hybrid_fwd4Args
    .private_segment_fixed_size: 0
    .sgpr_count:     108
    .sgpr_spill_count: 175
    .symbol:         _Z10hybrid_fwd4Args.kd
    .uniform_work_group_size: 1
    .uses_dynamic_stack: false
    .vgpr_count:     247
    .vgpr_spill_count: 0
    .wavefront_size: 64
